# sel: one static s_setprio 1 for waves 4-7 for the whole selected-branch phase (doc 7.4 lever, not tried on this phase before)
# speedup vs baseline: 1.0072x; 1.0072x over previous
; #define LAS __attribute__((address_space(3)))
; #define SEL_PREFETCH(pi) do { const int bg_ = (pi) >> 14, t_ = (pi) & (SEQ - 1), b_ = bg_ >> 1, g_ = bg_ & 1, cur_ = t_ >> 6; const size_t row_ = (size_t)b_ * SEQ + t_; \
;         idx_n = (lane < 16) ? IDX[(row_ * 2 + g_) * 16 + lane] : -1; \
;         } while (0)
; __device__ __forceinline__ void phase_sel(const Params& p, LAS unsigned char* lds, const bf16_t* Z, const float* G, const unsigned char* K8, const unsigned char* V8T, const float* ACC, const int* IDX, bf16_t* Mixed, int tid, int wid, int lane) {
;     const int cc = lane & 15, q4 = lane >> 4, hh = cc & 3;
;     const float c = 0.125f * LOG2E;
;     const int gw = p.bid * 8 + wid, NGW = p.gdim * 8;
;     int idx_n = -1, bg_staged = -1;
;     ...
;     if (gw < 4 * SEQ) SEL_PREFETCH(gw);
.LBB0_621:
	v_readlane_b32 s0, v254, 3
	v_readlane_b32 s1, v254, 4
	s_mov_b64 s[2:3], s[0:1]
	s_barrier
	s_barrier
	s_load_dwordx2 s[10:11], s[2:3], 0x88
	v_readlane_b32 s86, v254, 9
	v_readlane_b32 s4, v254, 0
	s_mov_b32 s9, s86
	v_mov_b32_e32 v5, v187
	s_movk_i32 s97, 0x1000
	v_readfirstlane_b32 s2, v5
	s_ashr_i32 s8, s2, 6
	s_cmp_lt_u32 s8, 4
	s_cbranch_scc1 .Lsel_noprio
	s_setprio 1
.Lsel_noprio:
	s_waitcnt lgkmcnt(0)
	s_add_u32 s2, s10, 0x1dc00000
	s_addc_u32 s3, s11, 0
	s_lshl_b32 s4, s4, 3
	s_add_i32 s24, s8, s4
	v_and_b32_e32 v4, 63, v5
	s_cmp_lt_i32 s24, 0x10000
	s_cselect_b64 s[4:5], -1, 0
	v_cmp_gt_u32_e64 s[38:39], 16, v4
	s_and_b64 s[12:13], s[4:5], s[38:39]
	v_mov_b32_e32 v246, -1
	v_lshlrev_b32_e32 v2, 2, v4
	v_readlane_b32 s87, v254, 10
	s_and_saveexec_b64 s[6:7], s[12:13]
	s_cbranch_execz .LBB0_623
	s_ashr_i32 s12, s24, 15
	s_ashr_i32 s13, s12, 31
	s_lshl_b32 s15, s24, 1
	s_lshl_b64 s[12:13], s[12:13], 15
	s_and_b32 s15, s15, 0x7ffe
	s_bfe_u32 s14, s24, 0x1000e
	s_or_b32 s12, s12, s15
	s_or_b32 s12, s12, s14
	s_lshl_b64 s[12:13], s[12:13], 6
	s_add_u32 s12, s2, s12
	s_addc_u32 s13, s3, s13
	global_load_dword v246, v2, s[12:13]

; __device__ __forceinline__ unsigned xb_add(unsigned* p, unsigned v) { return __hip_atomic_fetch_add(p, v, __ATOMIC_RELAXED, __HIP_MEMORY_SCOPE_AGENT); }
; __device__ __forceinline__ void xcd_barrier(const XcdBarrier& b) {
;     asm volatile("s_waitcnt vmcnt(0)" ::: "memory");
;     __syncthreads();
;     if (threadIdx.x == 0) {
;         unsigned* bar = b.bar;
;         __builtin_amdgcn_s_waitcnt(0);
;         unsigned nloc = b.st[0], nx = b.st[1];
;         if (nloc == 0u) { xcd_barrier_complete(bar, b.x, nloc, nx); b.st[0] = nloc; b.st[1] = nx; }
;         const unsigned old = xb_add(&bar[XB_XSUB(b.x)], 1u);
;         const unsigned gen = old / nloc;
;         if (old + 1u == (gen + 1u) * nloc) {
.LBB0_817:
	s_setprio 0
	v_readlane_b32 s2, v255, 6
	s_add_i32 s18, s2, 5
	s_cmp_lt_i32 s18, s89
	v_readlane_b32 s4, v254, 1
	s_cselect_b64 s[2:3], -1, 0
	v_readlane_b32 s5, v254, 2
	s_and_b64 s[2:3], s[4:5], s[2:3]
	v_readlane_b32 s44, v254, 58
	v_readlane_b32 s40, v254, 60
	v_readlane_b32 s46, v254, 62
	v_readlane_b32 s48, v255, 0
	v_readlane_b32 s50, v255, 2
	s_andn2_b64 vcc, exec, s[2:3]
	v_readlane_b32 s39, v254, 57
	v_readlane_b32 s45, v254, 59
	v_readlane_b32 s41, v254, 61
	v_readlane_b32 s47, v254, 63
	v_readlane_b32 s49, v255, 1
	v_readlane_b32 s51, v255, 3
	s_cbranch_vccnz .LBB0_862
	s_waitcnt vmcnt(0)
	s_waitcnt lgkmcnt(0)
	s_barrier
	s_mov_b64 s[2:3], exec
	v_readlane_b32 s4, v254, 53
	v_readlane_b32 s5, v254, 54
	s_and_b64 s[4:5], s[2:3], s[4:5]
	s_mov_b64 exec, s[4:5]
	s_cbranch_execz .LBB0_861
	v_readlane_b32 s4, v254, 51
	s_waitcnt vmcnt(0) expcnt(0) lgkmcnt(0)
	s_nop 0
	v_mov_b32_e32 v0, s4
	ds_read_b32 v3, v0
	v_readlane_b32 s4, v254, 52
	s_waitcnt lgkmcnt(0)
	v_cmp_ne_u32_e32 vcc, 0, v3
	v_mov_b32_e32 v0, s4
	ds_read_b32 v2, v0
	s_cbranch_vccnz .LBB0_832
	s_mov_b32 s10, 1
	s_branch .LBB0_822
